# spatial-gating item: eight dwordx2 gate-operand loads widened to four dwordx4 loads redistributed with v_permlane16_swap, counted waits recomputed
# speedup vs baseline: 1.0018x; 1.0018x over previous
; #define LAS __attribute__((address_space(3)))
; #define OPQV(x) asm volatile("" : "+v"(x))
; DEV void sgu_item(LAS unsigned char* lds, const bf16_t* P, const bf16_t* VN, const float* sgu_w, const float* sgu_b, bf16_t* OC, int item) {
;     int tid = threadIdx.x; OPQV(tid); const int lane = tid & 63, wv = tid >> 6, fr = lane & 15, g4 = lane >> 4;
;     LAS bf16_t* VT = (LAS bf16_t*)lds;
;     const int g = item & 7, ch = (item >> 3) & 15, b = item >> 7;
;     const size_t tok0 = (size_t)b * S_ + ch * 128;
;     const int t = wv * 16 + fr;
;     const size_t tok = tok0 + t;
;     u32x4 vin[4];
; #pragma unroll
;     for (int it = 0; it < 4; ++it) { const int idx = it * 512 + tid, s = idx >> 4, c8 = (idx & 15) * 8; vin[it] = *(const u32x4*)(VN + (tok0 + s) * 1024 + g * 128 + c8); }
;     const float* wrow = sgu_w + ((size_t)g * 128 + t) * 128;
;     f32x4 wa[4], wb[4];
; #pragma unroll
;     for (int ks = 0; ks < 4; ++ks) { wa[ks] = *(const f32x4*)(wrow + ks * 32 + g4 * 8); wb[ks] = *(const f32x4*)(wrow + ks * 32 + g4 * 8 + 4); }
;     u32x2 uu[8];
; #pragma unroll
;     for (int n = 0; n < 8; ++n) uu[n] = *(const u32x2*)(P + tok * NP + COL_U + g * 128 + n * 16 + g4 * 4);
;     const float bias = sgu_b[g * 128 + t];
; #pragma unroll
;     for (int it = 0; it < 4; ++it) { const int idx = it * 512 + tid, s = idx >> 4, c8 = (idx & 15) * 8;
; #pragma unroll
;         for (int j = 0; j < 4; ++j) { VT[(c8 + 2 * j) * 136 + s] = (bf16_t)(vin[it][j] & 0xffffu); VT[(c8 + 2 * j + 1) * 136 + s] = (bf16_t)(vin[it][j] >> 16); } }
;     __syncthreads();
; DEV void phase_mix(LAS unsigned char* lds, const bf16_t* P, const bf16_t* QB, const bf16_t* KV, const bf16_t* KC, const bf16_t* VC, const float* rel_bias, bf16_t* OB,
;                    const bf16_t* VN, const float* sgu_w, const float* sgu_b, bf16_t* OC, int* ctr) {
;     ...
;     for (;;) {
;         if (tid == 0) *(LAS int*)(lds + AT_NEXT) = atomicAdd(ctr, 1);
;         __syncthreads();
;         const int i = *(const LAS int*)(lds + AT_NEXT);
;         __syncthreads();
;         if (i >= 2048) break;
;         if (i < 1024) attn_item(lds, P, QB, KV, KC, VC, rel_bias, OB, (i & 31) >> 2, i & 3, 31 - (i >> 5));
;         else sgu_item(lds, P, VN, sgu_w, sgu_b, OC, i - 1024);
.LBB0_164:
	s_or_b64 exec, exec, s[4:5]
	v_mov_b32_e32 v0, s95
	s_waitcnt lgkmcnt(0)
	s_barrier
	ds_read_b32 v0, v0
	s_movk_i32 s4, 0x7ff
	s_waitcnt lgkmcnt(0)
	s_barrier
	v_cmp_lt_i32_e32 vcc, s4, v0
	v_readfirstlane_b32 s43, v0
	s_mov_b64 s[4:5], -1
	s_cbranch_vccnz .LBB0_159
	s_cmpk_gt_i32 s43, 0x3ff
	s_cbranch_scc0 .LBB0_167
	s_add_i32 s4, s43, 0xfffffc00
	s_lshl_b32 s5, s4, 4
	s_lshl_b32 s4, s4, 7
	v_mov_b32_e32 v8, v210
	s_and_b32 s6, s4, 0x380
	s_and_b32 s36, s5, 0x3f80
	v_lshlrev_b32_e32 v0, 3, v8
	s_lshl_b32 s4, s6, 1
	v_and_b32_e32 v9, 0x78, v0
	s_add_u32 s44, s34, s4
	v_ashrrev_i32_e32 v4, 4, v8
	s_addc_u32 s45, s35, 0
	v_lshlrev_b32_e32 v0, 1, v9
	v_ashrrev_i32_e32 v5, 31, v4
	v_lshl_add_u64 v[2:3], s[44:45], 0, v[0:1]
	v_lshl_add_u64 v[6:7], v[4:5], 0, s[36:37]
	v_add_u32_e32 v0, 0x200, v8
	v_lshlrev_b64 v[6:7], 11, v[6:7]
	v_ashrrev_i32_e32 v70, 4, v0
	v_lshl_add_u64 v[6:7], v[2:3], 0, v[6:7]
	v_ashrrev_i32_e32 v71, 31, v70
	global_load_dwordx4 v[30:33], v[6:7], off
	v_lshl_add_u64 v[6:7], v[70:71], 0, s[36:37]
	v_add_u32_e32 v0, 0x400, v8
	v_lshlrev_b64 v[6:7], 11, v[6:7]
	v_ashrrev_i32_e32 v72, 4, v0
	v_lshl_add_u64 v[6:7], v[2:3], 0, v[6:7]
	v_ashrrev_i32_e32 v73, 31, v72
	global_load_dwordx4 v[34:37], v[6:7], off
	v_lshl_add_u64 v[6:7], v[72:73], 0, s[36:37]
	v_add_u32_e32 v0, 0x600, v8
	v_lshlrev_b64 v[6:7], 11, v[6:7]
	v_ashrrev_i32_e32 v74, 4, v0
	v_lshl_add_u64 v[6:7], v[2:3], 0, v[6:7]
	v_ashrrev_i32_e32 v75, 31, v74
	global_load_dwordx4 v[38:41], v[6:7], off
	v_lshl_add_u64 v[6:7], v[74:75], 0, s[36:37]
	v_ashrrev_i32_e32 v0, 2, v8
	v_lshlrev_b64 v[6:7], 11, v[6:7]
	s_waitcnt vmcnt(11)
	v_bfi_b32 v28, -16, v0, v8
	v_lshl_add_u64 v[2:3], v[2:3], 0, v[6:7]
	v_ashrrev_i32_e32 v29, 31, v28
	s_mov_b32 s7, s37
	global_load_dwordx4 v[42:45], v[2:3], off
	v_lshl_add_u64 v[2:3], v[28:29], 0, s[6:7]
	v_bfe_u32 v0, v8, 4, 2
	v_lshlrev_b64 v[2:3], 9, v[2:3]
	v_lshl_add_u64 v[2:3], s[80:81], 0, v[2:3]
	v_lshlrev_b32_e32 v6, 5, v0
	v_mov_b32_e32 v7, v1
	v_lshl_add_u64 v[6:7], v[2:3], 0, v[6:7]
	global_load_dwordx4 v[46:49], v[6:7], off
	global_load_dwordx4 v[50:53], v[6:7], off offset:16
	v_mov_b64_e32 v[2:3], s[76:77]
	v_and_b32_e32 v82, 15, v8
	v_add_u32_e32 v8, s6, v28
	s_movk_i32 s6, 0x110
	v_lshl_add_u64 v[24:25], v[28:29], 0, s[36:37]
	s_mov_b32 s5, s37
	v_mad_u32_u24 v71, v9, s6, 0
	v_ashrrev_i32_e32 v9, 31, v8
	v_mad_i64_i32 v[2:3], s[6:7], v24, s59, v[2:3]
	v_lshl_add_u32 v73, v4, 1, v71
	v_lshlrev_b32_e32 v0, 3, v0
	v_lshl_add_u64 v[4:5], v[8:9], 2, s[82:83]
	v_lshl_add_u64 v[2:3], v[2:3], 0, s[4:5]
	global_load_dword v29, v[4:5], off
	v_lshl_add_u64 v[10:11], v[2:3], 0, v[0:1]
	global_load_dwordx4 v[54:57], v[6:7], off offset:144
	global_load_dwordx4 v[58:61], v[6:7], off offset:128
	global_load_dwordx4 v[62:65], v[6:7], off offset:272
	global_load_dwordx4 v[66:69], v[6:7], off offset:256
	global_load_dwordx4 v[2:5], v[6:7], off offset:400
	s_nop 0
	global_load_dwordx4 v[6:9], v[6:7], off offset:384
	s_mov_b64 s[6:7], 0x2c00
	s_movk_i32 s5, 0x2000
	v_lshl_add_u64 v[76:77], v[10:11], 0, s[6:7]
	v_and_b32_e32 v120, 16, v213
	v_lshrrev_b32_e32 v121, 1, v120
	v_add_u32_e32 v120, v120, v121
	v_mov_b32_e32 v121, 0
	v_lshl_add_u64 v[138:139], v[76:77], 0, v[120:121]
	v_add_co_u32_e32 v10, vcc, s5, v10
	v_or_b32_e32 v90, 32, v0
	s_nop 0
	v_addc_co_u32_e32 v11, vcc, 0, v11, vcc
	global_load_dwordx4 v[122:125], v[138:139], off
	global_load_dwordx4 v[126:129], v[138:139], off offset:64
	global_load_dwordx4 v[130:133], v[138:139], off offset:128
	global_load_dwordx4 v[134:137], v[138:139], off offset:192
	s_nop 0
	v_cmp_le_i32_e32 vcc, v0, v28
	v_or_b32_e32 v91, 33, v0
	s_movk_i32 s5, 0x88
	v_mad_u32_u24 v83, v82, s5, v227
	v_mad_u32_u24 v84, v82, s5, v252
	v_mad_u32_u24 v85, v82, s5, v216
	v_mad_u32_u24 v86, v82, s5, v217
	v_mad_u32_u24 v87, v82, s5, v218
	s_waitcnt vmcnt(16)
	ds_write_b16 v73, v30
	ds_write_b16_d16_hi v73, v30 offset:272
	ds_write_b16 v73, v31 offset:544
	ds_write_b16_d16_hi v73, v31 offset:816
	ds_write_b16 v73, v32 offset:1088
	ds_write_b16_d16_hi v73, v32 offset:1360
	ds_write_b16 v73, v33 offset:1632
	ds_write_b16_d16_hi v73, v33 offset:1904
	v_lshl_add_u32 v30, v70, 1, v71
	s_waitcnt vmcnt(15)
	ds_write_b16 v30, v34
	ds_write_b16_d16_hi v30, v34 offset:272
	ds_write_b16 v30, v35 offset:544
	ds_write_b16_d16_hi v30, v35 offset:816
	ds_write_b16 v30, v36 offset:1088
	ds_write_b16_d16_hi v30, v36 offset:1360
	ds_write_b16 v30, v37 offset:1632
	ds_write_b16_d16_hi v30, v37 offset:1904
	v_lshl_add_u32 v30, v72, 1, v71
	s_waitcnt vmcnt(14)
	ds_write_b16 v30, v38
	ds_write_b16_d16_hi v30, v38 offset:272
	ds_write_b16 v30, v39 offset:544
	ds_write_b16_d16_hi v30, v39 offset:816
	ds_write_b16 v30, v40 offset:1088
	ds_write_b16_d16_hi v30, v40 offset:1360
	ds_write_b16 v30, v41 offset:1632
	ds_write_b16_d16_hi v30, v41 offset:1904
	v_lshl_add_u32 v30, v74, 1, v71
	s_waitcnt vmcnt(13)
	ds_write_b16 v30, v42
	ds_write_b16_d16_hi v30, v42 offset:272
	ds_write_b16 v30, v43 offset:544
	ds_write_b16_d16_hi v30, v43 offset:816
	ds_write_b16 v30, v44 offset:1088
	ds_write_b16_d16_hi v30, v44 offset:1360
	ds_write_b16 v30, v45 offset:1632
	ds_write_b16_d16_hi v30, v45 offset:1904
	v_or_b32_e32 v32, 2, v0
	v_or_b32_e32 v33, 3, v0
	v_or_b32_e32 v34, 4, v0
	v_or_b32_e32 v35, 5, v0
	v_or_b32_e32 v36, 6, v0
	v_or_b32_e32 v37, 7, v0
	s_waitcnt vmcnt(12) lgkmcnt(0)
	v_cndmask_b32_e32 v30, 0, v46, vcc
	v_cmp_lt_i32_e32 vcc, v0, v28
	s_barrier
; #define LAS __attribute__((address_space(3)))
; DEV u32x4 pack8(const float (&f)[8]) { u32x4 w; w.x = cvt_pk_bf16(f[0], f[1]); w.y = cvt_pk_bf16(f[2], f[3]); w.z = cvt_pk_bf16(f[4], f[5]); w.w = cvt_pk_bf16(f[6], f[7]); return w; }
; DEV void sgu_item(LAS unsigned char* lds, const bf16_t* P, const bf16_t* VN, const float* sgu_w, const float* sgu_b, bf16_t* OC, int item) {
;     ...
; #pragma unroll
;     for (int ks = 0; ks < 4; ++ks) { const int s0 = ks * 32 + g4 * 8;
;         float wf[8] = {wa[ks][0], wa[ks][1], wa[ks][2], wa[ks][3], wb[ks][0], wb[ks][1], wb[ks][2], wb[ks][3]};
; #pragma unroll
;         for (int j = 0; j < 8; ++j) if (s0 + j > t) wf[j] = 0.f;
;         const bf16x8 wfr = as_bf16x8(pack8(wf));
; #pragma unroll
;         for (int n = 0; n < 8; ++n) { const bf16x8 vf = *(const LAS bf16x8*)(lds + ((n * 16 + fr) * 136 + s0) * 2);
;             acc[n] = __builtin_amdgcn_mfma_f32_16x16x32_bf16(vf, wfr, acc[n], 0, 0, 0); } }
	s_nop 0
	v_cndmask_b32_e32 v31, 0, v47, vcc
	v_cmp_le_i32_e32 vcc, v32, v28
	v_cvt_pk_bf16_f32 v30, v30, v31
	v_mad_u32_u24 v88, v82, s5, v219
	v_mad_u32_u24 v89, v82, s5, v220
	v_cndmask_b32_e32 v32, 0, v48, vcc
	v_cmp_le_i32_e32 vcc, v33, v28
	v_add_u32_e32 v38, v83, v0
	v_add_u32_e32 v42, v84, v0
	v_cndmask_b32_e32 v33, 0, v49, vcc
	v_cmp_le_i32_e32 vcc, v34, v28
	v_cvt_pk_bf16_f32 v31, v32, v33
	v_add_u32_e32 v46, v85, v0
	v_add_u32_e32 v70, v87, v0
	s_waitcnt vmcnt(11)
	v_cndmask_b32_e32 v34, 0, v50, vcc
	v_cmp_le_i32_e32 vcc, v35, v28
	v_add_u32_e32 v50, v86, v0
	v_add_u32_e32 v74, v88, v0
	v_cndmask_b32_e32 v35, 0, v51, vcc
	v_cmp_le_i32_e32 vcc, v36, v28
	v_cvt_pk_bf16_f32 v32, v34, v35
	v_mad_u32_u24 v34, v82, s5, v0
	v_lshl_add_u32 v34, v34, 1, 0
	v_cndmask_b32_e32 v36, 0, v52, vcc
	v_cmp_le_i32_e32 vcc, v37, v28
	v_add_u32_e32 v78, v89, v0
	v_lshl_add_u32 v38, v38, 1, 0
	v_cndmask_b32_e32 v37, 0, v53, vcc
	v_cmp_le_i32_e32 vcc, v90, v28
	v_cvt_pk_bf16_f32 v33, v36, v37
	ds_read_b128 v[34:37], v34
	ds_read_b128 v[38:41], v38
	s_waitcnt vmcnt(8)
	v_cndmask_b32_e32 v58, 0, v58, vcc
	v_cmp_le_i32_e32 vcc, v91, v28
	v_or_b32_e32 v91, 34, v0
	v_lshl_add_u32 v42, v42, 1, 0
	v_cndmask_b32_e32 v59, 0, v59, vcc
	v_cmp_le_i32_e32 vcc, v91, v28
	v_or_b32_e32 v91, 35, v0
	v_lshl_add_u32 v46, v46, 1, 0
	v_cndmask_b32_e32 v60, 0, v60, vcc
	v_cmp_le_i32_e32 vcc, v91, v28
	v_or_b32_e32 v91, 36, v0
	v_lshl_add_u32 v50, v50, 1, 0
	v_cndmask_b32_e32 v61, 0, v61, vcc
	v_cmp_le_i32_e32 vcc, v91, v28
	v_lshl_add_u32 v70, v70, 1, 0
	v_lshl_add_u32 v74, v74, 1, 0
	v_cndmask_b32_e32 v91, 0, v54, vcc
	v_or_b32_e32 v54, 37, v0
	v_cmp_le_i32_e32 vcc, v54, v28
	v_or_b32_e32 v54, 38, v0
	v_lshl_add_u32 v78, v78, 1, 0
	v_cndmask_b32_e32 v92, 0, v55, vcc
	v_cmp_le_i32_e32 vcc, v54, v28
	v_or_b32_e32 v54, 39, v0
	ds_read_b128 v[42:45], v42
	ds_read_b128 v[46:49], v46
	ds_read_b128 v[50:53], v50
	ds_read_b128 v[70:73], v70
	ds_read_b128 v[74:77], v74
	ds_read_b128 v[78:81], v78
	v_cndmask_b32_e32 v93, 0, v56, vcc
	v_cmp_le_i32_e32 vcc, v54, v28
	v_cvt_pk_bf16_f32 v54, v58, v59
	v_mad_u32_u24 v58, v82, s5, v90
	v_lshl_add_u32 v58, v58, 1, 0
	v_cndmask_b32_e32 v57, 0, v57, vcc
	v_cvt_pk_bf16_f32 v55, v60, v61
	v_cvt_pk_bf16_f32 v56, v91, v92
	v_cvt_pk_bf16_f32 v57, v93, v57
	ds_read_b128 v[58:61], v58
	s_waitcnt lgkmcnt(8)
	v_mfma_f32_16x16x32_bf16 v[34:37], v[34:37], v[30:33], 0
	v_lshlrev_b64 v[24:25], 11, v[24:25]
	v_lshl_add_u64 v[24:25], s[88:89], 0, v[24:25]
	s_waitcnt lgkmcnt(7)
	v_mfma_f32_16x16x32_bf16 v[38:41], v[38:41], v[30:33], 0
	s_waitcnt lgkmcnt(6)
	v_mfma_f32_16x16x32_bf16 v[42:45], v[42:45], v[30:33], 0
	s_waitcnt lgkmcnt(5)
	v_mfma_f32_16x16x32_bf16 v[46:49], v[46:49], v[30:33], 0
	s_waitcnt lgkmcnt(4)
	v_mfma_f32_16x16x32_bf16 v[50:53], v[50:53], v[30:33], 0
	s_waitcnt lgkmcnt(3)
	v_mfma_f32_16x16x32_bf16 v[70:73], v[70:73], v[30:33], 0
	s_waitcnt lgkmcnt(2)
	v_mfma_f32_16x16x32_bf16 v[74:77], v[74:77], v[30:33], 0
	s_waitcnt lgkmcnt(1)
	v_mfma_f32_16x16x32_bf16 v[30:33], v[78:81], v[30:33], 0
	v_add_u32_e32 v78, v90, v83
	v_lshl_add_u32 v78, v78, 1, 0
	ds_read_b128 v[78:81], v78
	s_waitcnt lgkmcnt(1)
	v_mfma_f32_16x16x32_bf16 v[34:37], v[58:61], v[54:57], v[34:37]
	v_add_u32_e32 v58, v90, v84
	v_lshl_add_u32 v58, v58, 1, 0
	ds_read_b128 v[58:61], v58
	s_waitcnt lgkmcnt(1)
	v_mfma_f32_16x16x32_bf16 v[38:41], v[78:81], v[54:57], v[38:41]
	v_add_u32_e32 v78, v90, v85
	v_lshl_add_u32 v78, v78, 1, 0
	ds_read_b128 v[78:81], v78
	s_waitcnt lgkmcnt(1)
	v_mfma_f32_16x16x32_bf16 v[42:45], v[58:61], v[54:57], v[42:45]
	v_add_u32_e32 v58, v90, v86
	v_lshl_add_u32 v58, v58, 1, 0
	ds_read_b128 v[58:61], v58
	s_waitcnt lgkmcnt(1)
	v_mfma_f32_16x16x32_bf16 v[46:49], v[78:81], v[54:57], v[46:49]
	v_add_u32_e32 v78, v90, v87
	v_lshl_add_u32 v78, v78, 1, 0
	ds_read_b128 v[78:81], v78
	s_waitcnt lgkmcnt(1)
	v_mfma_f32_16x16x32_bf16 v[50:53], v[58:61], v[54:57], v[50:53]
	v_add_u32_e32 v58, v90, v88
	v_lshl_add_u32 v58, v58, 1, 0
	ds_read_b128 v[58:61], v58
	s_waitcnt lgkmcnt(1)
	v_mfma_f32_16x16x32_bf16 v[70:73], v[78:81], v[54:57], v[70:73]
	v_add_u32_e32 v78, v90, v89
	v_lshl_add_u32 v78, v78, 1, 0
	ds_read_b128 v[78:81], v78
	s_waitcnt lgkmcnt(1)
	v_mfma_f32_16x16x32_bf16 v[58:61], v[58:61], v[54:57], v[74:77]
	s_nop 2
	v_or_b32_e32 v74, 64, v0
	v_cmp_le_i32_e32 vcc, v74, v28
	v_or_b32_e32 v75, 0x41, v0
	s_waitcnt lgkmcnt(0)
	v_mfma_f32_16x16x32_bf16 v[30:33], v[78:81], v[54:57], v[30:33]
	s_waitcnt vmcnt(6)
	v_cndmask_b32_e32 v66, 0, v66, vcc
	v_cmp_le_i32_e32 vcc, v75, v28
	v_or_b32_e32 v75, 0x42, v0
	v_add_u32_e32 v54, v74, v83
	v_cndmask_b32_e32 v67, 0, v67, vcc
	v_cmp_le_i32_e32 vcc, v75, v28
	v_or_b32_e32 v75, 0x43, v0
	v_lshl_add_u32 v54, v54, 1, 0
	v_cndmask_b32_e32 v68, 0, v68, vcc
	v_cmp_le_i32_e32 vcc, v75, v28
	v_or_b32_e32 v75, 0x44, v0
	s_nop 0
	v_cndmask_b32_e32 v69, 0, v69, vcc
	v_cmp_le_i32_e32 vcc, v75, v28
	s_nop 1
	v_cndmask_b32_e32 v75, 0, v62, vcc
	v_or_b32_e32 v62, 0x45, v0
	v_cmp_le_i32_e32 vcc, v62, v28
	v_or_b32_e32 v62, 0x46, v0
	s_nop 0
	v_cndmask_b32_e32 v76, 0, v63, vcc
	v_cmp_le_i32_e32 vcc, v62, v28
	v_or_b32_e32 v62, 0x47, v0
	s_nop 0
	v_cndmask_b32_e32 v77, 0, v64, vcc
	v_cmp_le_i32_e32 vcc, v62, v28
	v_cvt_pk_bf16_f32 v62, v66, v67
	v_mad_u32_u24 v66, v82, s5, v74
	v_lshl_add_u32 v66, v66, 1, 0
	v_cndmask_b32_e32 v65, 0, v65, vcc
	v_cvt_pk_bf16_f32 v63, v68, v69
	v_cvt_pk_bf16_f32 v64, v75, v76
	v_cvt_pk_bf16_f32 v65, v77, v65
	ds_read_b128 v[66:69], v66
	ds_read_b128 v[54:57], v54
	s_waitcnt lgkmcnt(1)
	v_mfma_f32_16x16x32_bf16 v[34:37], v[66:69], v[62:65], v[34:37]
	v_add_u32_e32 v66, v74, v84
	v_lshl_add_u32 v66, v66, 1, 0
	ds_read_b128 v[66:69], v66
	s_waitcnt lgkmcnt(1)
; #define LAS __attribute__((address_space(3)))
; DEV float bflo(unsigned u) { return __uint_as_float(u << 16); }
; DEV float bfhi(unsigned u) { return __uint_as_float(u & 0xffff0000u); }
; DEV unsigned cvt_pk_bf16(float lo, float hi) { unsigned r; asm volatile("v_cvt_pk_bf16_f32 %0, %1, %2" : "=v"(r) : "v"(lo), "v"(hi)); return r; }
; DEV u32x4 pack8(const float (&f)[8]) { u32x4 w; w.x = cvt_pk_bf16(f[0], f[1]); w.y = cvt_pk_bf16(f[2], f[3]); w.z = cvt_pk_bf16(f[4], f[5]); w.w = cvt_pk_bf16(f[6], f[7]); return w; }
; DEV void sgu_item(LAS unsigned char* lds, const bf16_t* P, const bf16_t* VN, const float* sgu_w, const float* sgu_b, bf16_t* OC, int item) {
;     ...
;     for (int ks = 0; ks < 4; ++ks) { const int s0 = ks * 32 + g4 * 8;
;         float wf[8] = {wa[ks][0], wa[ks][1], wa[ks][2], wa[ks][3], wb[ks][0], wb[ks][1], wb[ks][2], wb[ks][3]};
; #pragma unroll
;         for (int j = 0; j < 8; ++j) if (s0 + j > t) wf[j] = 0.f;
;         const bf16x8 wfr = as_bf16x8(pack8(wf));
; #pragma unroll
;         for (int n = 0; n < 8; ++n) { const bf16x8 vf = *(const LAS bf16x8*)(lds + ((n * 16 + fr) * 136 + s0) * 2);
;             acc[n] = __builtin_amdgcn_mfma_f32_16x16x32_bf16(vf, wfr, acc[n], 0, 0, 0); } }
; #pragma unroll
;     for (int n = 0; n < 8; ++n) { const int c = g * 128 + n * 16 + g4 * 4;
;         u32x2 w; w.x = cvt_pk_bf16(bflo(uu[n].x) * (acc[n][0] + bias), bfhi(uu[n].x) * (acc[n][1] + bias)); w.y = cvt_pk_bf16(bflo(uu[n].y) * (acc[n][2] + bias), bfhi(uu[n].y) * (acc[n][3] + bias));
;         *(u32x2*)(OC + tok * 1024 + c) = w; }
	v_mfma_f32_16x16x32_bf16 v[38:41], v[54:57], v[62:65], v[38:41]
	v_add_u32_e32 v54, v74, v85
	v_lshl_add_u32 v54, v54, 1, 0
	ds_read_b128 v[54:57], v54
	s_waitcnt lgkmcnt(1)
	v_mfma_f32_16x16x32_bf16 v[42:45], v[66:69], v[62:65], v[42:45]
	v_add_u32_e32 v66, v74, v86
	v_lshl_add_u32 v66, v66, 1, 0
	ds_read_b128 v[66:69], v66
	s_waitcnt lgkmcnt(1)
	v_mfma_f32_16x16x32_bf16 v[46:49], v[54:57], v[62:65], v[46:49]
	v_add_u32_e32 v54, v74, v87
	v_lshl_add_u32 v54, v54, 1, 0
	ds_read_b128 v[54:57], v54
	s_waitcnt lgkmcnt(1)
	v_mfma_f32_16x16x32_bf16 v[50:53], v[66:69], v[62:65], v[50:53]
	v_add_u32_e32 v66, v74, v88
	v_lshl_add_u32 v66, v66, 1, 0
	ds_read_b128 v[66:69], v66
	s_waitcnt lgkmcnt(1)
	v_mfma_f32_16x16x32_bf16 v[54:57], v[54:57], v[62:65], v[70:73]
	s_nop 2
	v_add_u32_e32 v70, v74, v89
	v_lshl_add_u32 v70, v70, 1, 0
	ds_read_b128 v[70:73], v70
	s_waitcnt lgkmcnt(1)
	v_mfma_f32_16x16x32_bf16 v[58:61], v[66:69], v[62:65], v[58:61]
	v_or_b32_e32 v66, 0x60, v0
	v_cmp_le_i32_e32 vcc, v66, v28
	v_or_b32_e32 v67, 0x61, v0
	s_waitcnt lgkmcnt(0)
	v_mfma_f32_16x16x32_bf16 v[30:33], v[70:73], v[62:65], v[30:33]
	s_waitcnt vmcnt(4)
	v_cndmask_b32_e32 v6, 0, v6, vcc
	v_cmp_le_i32_e32 vcc, v67, v28
	v_or_b32_e32 v67, 0x62, v0
	s_nop 0
	v_cndmask_b32_e32 v7, 0, v7, vcc
	v_cmp_le_i32_e32 vcc, v67, v28
	v_or_b32_e32 v67, 0x63, v0
	s_nop 0
	v_cndmask_b32_e32 v8, 0, v8, vcc
	v_cmp_le_i32_e32 vcc, v67, v28
	v_or_b32_e32 v67, 0x64, v0
	s_nop 0
	v_cndmask_b32_e32 v9, 0, v9, vcc
	v_cmp_le_i32_e32 vcc, v67, v28
	s_nop 1
	v_cndmask_b32_e32 v67, 0, v2, vcc
	v_or_b32_e32 v2, 0x65, v0
	v_cmp_le_i32_e32 vcc, v2, v28
	v_or_b32_e32 v2, 0x66, v0
	s_nop 0
	v_cndmask_b32_e32 v68, 0, v3, vcc
	v_cmp_le_i32_e32 vcc, v2, v28
	v_or_b32_e32 v2, 0x67, v0
	v_or_b32_e32 v0, s4, v0
	v_cndmask_b32_e32 v69, 0, v4, vcc
	v_cmp_le_i32_e32 vcc, v2, v28
	v_cvt_pk_bf16_f32 v2, v6, v7
	v_mad_u32_u24 v6, v82, s5, v66
	v_lshl_add_u32 v6, v6, 1, 0
	v_cndmask_b32_e32 v5, 0, v5, vcc
	v_cvt_pk_bf16_f32 v3, v8, v9
	v_cvt_pk_bf16_f32 v4, v67, v68
	v_cvt_pk_bf16_f32 v5, v69, v5
	ds_read_b128 v[6:9], v6
	v_add_u32_e32 v28, v66, v83
	v_lshl_add_u32 v28, v28, 1, 0
	ds_read_b128 v[62:65], v28
	v_add_u32_e32 v28, v66, v84
	v_lshl_add_u32 v28, v28, 1, 0
	s_waitcnt lgkmcnt(1)
	v_mfma_f32_16x16x32_bf16 v[6:9], v[6:9], v[2:5], v[34:37]
	s_nop 2
	ds_read_b128 v[34:37], v28
	v_add_u32_e32 v28, v66, v85
	v_lshl_add_u32 v28, v28, 1, 0
	s_waitcnt lgkmcnt(1)
	v_mfma_f32_16x16x32_bf16 v[38:41], v[62:65], v[2:5], v[38:41]
	ds_read_b128 v[62:65], v28
	v_add_u32_e32 v28, v66, v86
	v_lshl_add_u32 v28, v28, 1, 0
	s_waitcnt lgkmcnt(1)
	v_mfma_f32_16x16x32_bf16 v[34:37], v[34:37], v[2:5], v[42:45]
	v_add_f32_e32 v6, v29, v6
	s_nop 1
	ds_read_b128 v[42:45], v28
	v_add_u32_e32 v28, v66, v87
	v_lshl_add_u32 v28, v28, 1, 0
	s_waitcnt lgkmcnt(1)
	v_mfma_f32_16x16x32_bf16 v[46:49], v[62:65], v[2:5], v[46:49]
	ds_read_b128 v[62:65], v28
	v_add_u32_e32 v28, v66, v88
	v_lshl_add_u32 v28, v28, 1, 0
	s_waitcnt lgkmcnt(1)
	v_mfma_f32_16x16x32_bf16 v[42:45], v[42:45], v[2:5], v[50:53]
	v_add_f32_e32 v7, v29, v7
	s_nop 1
	ds_read_b128 v[50:53], v28
	v_add_u32_e32 v28, v66, v89
	v_lshl_add_u32 v28, v28, 1, 0
	s_waitcnt lgkmcnt(1)
	v_mfma_f32_16x16x32_bf16 v[54:57], v[62:65], v[2:5], v[54:57]
	ds_read_b128 v[62:65], v28
	s_waitcnt vmcnt(3)
	v_permlane16_swap_b32_e32 v122, v124
	v_permlane16_swap_b32_e32 v123, v125
	v_lshlrev_b32_e32 v28, 16, v122
	v_and_b32_e32 v122, 0xffff0000, v122
	v_mul_f32_e32 v6, v6, v28
	v_mul_f32_e32 v7, v7, v122
	v_cvt_pk_bf16_f32 v104, v6, v7
	v_lshlrev_b32_e32 v7, 16, v123
	v_add_f32_e32 v8, v29, v8
	v_mul_f32_e32 v7, v8, v7
	v_and_b32_e32 v8, 0xffff0000, v123
	v_add_f32_e32 v9, v29, v9
	v_mul_f32_e32 v8, v9, v8
	v_cvt_pk_bf16_f32 v105, v7, v8
	v_lshl_add_u64 v[8:9], v[24:25], 0, v[0:1]
	v_and_b32_e32 v120, 16, v213
	v_lshrrev_b32_e32 v121, 1, v120
	v_add_u32_e32 v120, v120, v121
	v_add_co_u32_e32 v8, vcc, v8, v120
	s_nop 1
	v_addc_co_u32_e32 v9, vcc, 0, v9, vcc
	v_lshlrev_b32_e32 v0, 16, v124
	v_add_f32_e32 v6, v29, v38
	v_mul_f32_e32 v0, v6, v0
	v_and_b32_e32 v6, 0xffff0000, v124
	v_add_f32_e32 v7, v29, v39
	v_mul_f32_e32 v6, v7, v6
	v_cvt_pk_bf16_f32 v106, v0, v6
	v_lshlrev_b32_e32 v0, 16, v125
	v_add_f32_e32 v7, v29, v40
	v_mul_f32_e32 v0, v7, v0
	v_and_b32_e32 v7, 0xffff0000, v125
	v_add_f32_e32 v124, v29, v41
	v_mul_f32_e32 v7, v124, v7
	v_cvt_pk_bf16_f32 v107, v0, v7
	s_nop 1
	v_permlane16_swap_b32_e32 v104, v106
	v_permlane16_swap_b32_e32 v105, v107
	global_store_dwordx4 v[8:9], v[104:107], off
	s_waitcnt vmcnt(3)
; DEV float bflo(unsigned u) { return __uint_as_float(u << 16); }
; DEV float bfhi(unsigned u) { return __uint_as_float(u & 0xffff0000u); }
; DEV unsigned cvt_pk_bf16(float lo, float hi) { unsigned r; asm volatile("v_cvt_pk_bf16_f32 %0, %1, %2" : "=v"(r) : "v"(lo), "v"(hi)); return r; }
; DEV void sgu_item(LAS unsigned char* lds, const bf16_t* P, const bf16_t* VN, const float* sgu_w, const float* sgu_b, bf16_t* OC, int item) {
;     ...
; #pragma unroll
;     for (int n = 0; n < 8; ++n) { const int c = g * 128 + n * 16 + g4 * 4;
;         u32x2 w; w.x = cvt_pk_bf16(bflo(uu[n].x) * (acc[n][0] + bias), bfhi(uu[n].x) * (acc[n][1] + bias)); w.y = cvt_pk_bf16(bflo(uu[n].y) * (acc[n][2] + bias), bfhi(uu[n].y) * (acc[n][3] + bias));
;         *(u32x2*)(OC + tok * 1024 + c) = w; }
;     __syncthreads();
	v_permlane16_swap_b32_e32 v126, v128
	v_permlane16_swap_b32_e32 v127, v129
	v_lshlrev_b32_e32 v0, 16, v126
	v_add_f32_e32 v6, v29, v34
	v_mul_f32_e32 v0, v6, v0
	v_and_b32_e32 v6, 0xffff0000, v126
	v_add_f32_e32 v7, v29, v35
	v_mul_f32_e32 v6, v7, v6
	v_cvt_pk_bf16_f32 v108, v0, v6
	v_lshlrev_b32_e32 v0, 16, v127
	v_add_f32_e32 v7, v29, v36
	v_mul_f32_e32 v0, v7, v0
	v_and_b32_e32 v7, 0xffff0000, v127
	v_add_f32_e32 v126, v29, v37
	v_mul_f32_e32 v7, v126, v7
	v_cvt_pk_bf16_f32 v109, v0, v7
	v_lshlrev_b32_e32 v0, 16, v128
	v_add_f32_e32 v6, v29, v46
	v_mul_f32_e32 v0, v6, v0
	v_and_b32_e32 v6, 0xffff0000, v128
	v_add_f32_e32 v7, v29, v47
	v_mul_f32_e32 v6, v7, v6
	v_cvt_pk_bf16_f32 v110, v0, v6
	v_lshlrev_b32_e32 v0, 16, v129
	v_add_f32_e32 v7, v29, v48
	v_mul_f32_e32 v0, v7, v0
	v_and_b32_e32 v7, 0xffff0000, v129
	v_add_f32_e32 v128, v29, v49
	v_mul_f32_e32 v7, v128, v7
	v_cvt_pk_bf16_f32 v111, v0, v7
	s_nop 1
	v_permlane16_swap_b32_e32 v108, v110
	v_permlane16_swap_b32_e32 v109, v111
	global_store_dwordx4 v[8:9], v[108:111], off offset:64
	s_waitcnt vmcnt(3)
	v_permlane16_swap_b32_e32 v130, v132
	v_permlane16_swap_b32_e32 v131, v133
	v_lshlrev_b32_e32 v0, 16, v130
	v_add_f32_e32 v6, v29, v42
	v_mul_f32_e32 v0, v6, v0
	v_and_b32_e32 v6, 0xffff0000, v130
	v_add_f32_e32 v7, v29, v43
	v_mul_f32_e32 v6, v7, v6
	v_cvt_pk_bf16_f32 v112, v0, v6
	v_lshlrev_b32_e32 v0, 16, v131
	v_add_f32_e32 v7, v29, v44
	v_mul_f32_e32 v0, v7, v0
	v_and_b32_e32 v7, 0xffff0000, v131
	v_add_f32_e32 v130, v29, v45
	v_mul_f32_e32 v7, v130, v7
	v_cvt_pk_bf16_f32 v113, v0, v7
	s_waitcnt vmcnt(4)
	v_lshlrev_b32_e32 v0, 16, v132
	v_add_f32_e32 v6, v29, v54
	v_mul_f32_e32 v0, v6, v0
	v_and_b32_e32 v6, 0xffff0000, v132
	v_add_f32_e32 v7, v29, v55
	s_waitcnt lgkmcnt(1)
	v_mfma_f32_16x16x32_bf16 v[50:53], v[50:53], v[2:5], v[58:61]
	v_mul_f32_e32 v6, v7, v6
	v_cvt_pk_bf16_f32 v114, v0, v6
	v_lshlrev_b32_e32 v0, 16, v133
	v_add_f32_e32 v7, v29, v56
	v_mul_f32_e32 v0, v7, v0
	v_and_b32_e32 v7, 0xffff0000, v133
	v_add_f32_e32 v132, v29, v57
	v_mul_f32_e32 v7, v132, v7
	v_cvt_pk_bf16_f32 v115, v0, v7
	s_nop 1
	v_permlane16_swap_b32_e32 v112, v114
	v_permlane16_swap_b32_e32 v113, v115
	global_store_dwordx4 v[8:9], v[112:115], off offset:128
	s_waitcnt vmcnt(3)
	v_permlane16_swap_b32_e32 v134, v136
	v_permlane16_swap_b32_e32 v135, v137
	v_lshlrev_b32_e32 v0, 16, v134
	v_add_f32_e32 v6, v29, v50
	v_mul_f32_e32 v0, v6, v0
	v_and_b32_e32 v6, 0xffff0000, v134
	v_add_f32_e32 v7, v29, v51
	s_waitcnt lgkmcnt(0)
	v_mfma_f32_16x16x32_bf16 v[2:5], v[62:65], v[2:5], v[30:33]
	v_mul_f32_e32 v6, v7, v6
	v_cvt_pk_bf16_f32 v116, v0, v6
	v_lshlrev_b32_e32 v0, 16, v135
	v_add_f32_e32 v7, v29, v52
	v_mul_f32_e32 v0, v7, v0
	v_and_b32_e32 v7, 0xffff0000, v135
	v_add_f32_e32 v134, v29, v53
	v_mul_f32_e32 v7, v134, v7
	v_cvt_pk_bf16_f32 v117, v0, v7
	s_waitcnt vmcnt(3)
	v_lshlrev_b32_e32 v0, 16, v136
	v_add_f32_e32 v2, v29, v2
	v_mul_f32_e32 v0, v2, v0
	v_and_b32_e32 v2, 0xffff0000, v136
	v_add_f32_e32 v3, v29, v3
	v_mul_f32_e32 v2, v3, v2
	v_cvt_pk_bf16_f32 v118, v0, v2
	v_lshlrev_b32_e32 v0, 16, v137
	v_add_f32_e32 v3, v29, v4
	v_mul_f32_e32 v0, v3, v0
	v_and_b32_e32 v3, 0xffff0000, v137
	v_add_f32_e32 v4, v29, v5
	v_mul_f32_e32 v3, v4, v3
	v_cvt_pk_bf16_f32 v119, v0, v3
	s_nop 1
	v_permlane16_swap_b32_e32 v116, v118
	v_permlane16_swap_b32_e32 v117, v119
	global_store_dwordx4 v[8:9], v[116:119], off offset:192
	s_barrier
	s_mov_b64 s[4:5], 0
